# P0: LDS table fill fully unrolled (32 loads in flight) + transpose tile loads issued before the workgroup barrier
# baseline (speedup 1.0000x reference)
; DI void phase_prep(const Params& p, int bid, int nb, char* smem) {
;     ...
;   for (int i = tid; i < 8192; i += 256) { int k = i >> 3, j = i & 7; wabT[j * 1024 + k] = p.w_in[(size_t)k * INC + 3584 + j]; }
.LBB0_9:
	v_lshrrev_b32_e32 v154, 3, v4
	v_lshrrev_b32_e32 v155, 3, v5
	v_mad_u64_u32 v[150:151], s[4:5], v155, s3, v[2:3]
	v_mad_u64_u32 v[152:153], s[4:5], v154, s3, v[2:3]
	v_mov_b32_e32 v153, v7
	v_mov_b32_e32 v151, v7
	v_lshl_add_u64 v[152:153], v[152:153], 2, s[20:21]
	v_lshl_add_u64 v[150:151], v[150:151], 2, s[20:21]
	global_load_dword v152, v[152:153], off
	s_nop 0
	global_load_dword v150, v[150:151], off
	v_lshl_add_u32 v151, v154, 2, v3
	v_lshl_add_u32 v153, v155, 2, v3
	v_add_u32_e32 v156, 0x200, v5
	v_add_u32_e32 v157, 0x200, v4
	v_lshrrev_b32_e32 v160, 3, v157
	v_lshrrev_b32_e32 v161, 3, v156
	v_mad_u64_u32 v[156:157], s[4:5], v161, s3, v[2:3]
	v_mad_u64_u32 v[158:159], s[4:5], v160, s3, v[2:3]
	v_mov_b32_e32 v159, v7
	v_mov_b32_e32 v157, v7
	v_lshl_add_u64 v[158:159], v[158:159], 2, s[20:21]
	v_lshl_add_u64 v[156:157], v[156:157], 2, s[20:21]
	global_load_dword v158, v[158:159], off
	s_nop 0
	global_load_dword v156, v[156:157], off
	v_lshl_add_u32 v157, v160, 2, v3
	v_lshl_add_u32 v159, v161, 2, v3
	v_add_u32_e32 v162, 0x400, v5
	v_add_u32_e32 v163, 0x400, v4
	v_lshrrev_b32_e32 v166, 3, v163
	v_lshrrev_b32_e32 v167, 3, v162
	v_mad_u64_u32 v[162:163], s[4:5], v167, s3, v[2:3]
	v_mad_u64_u32 v[164:165], s[4:5], v166, s3, v[2:3]
	v_mov_b32_e32 v165, v7
	v_mov_b32_e32 v163, v7
	v_lshl_add_u64 v[164:165], v[164:165], 2, s[20:21]
	v_lshl_add_u64 v[162:163], v[162:163], 2, s[20:21]
	global_load_dword v164, v[164:165], off
	s_nop 0
	global_load_dword v162, v[162:163], off
	v_lshl_add_u32 v163, v166, 2, v3
	v_lshl_add_u32 v165, v167, 2, v3
	v_add_u32_e32 v168, 0x600, v5
	v_add_u32_e32 v169, 0x600, v4
	v_lshrrev_b32_e32 v172, 3, v169
	v_lshrrev_b32_e32 v173, 3, v168
	v_mad_u64_u32 v[168:169], s[4:5], v173, s3, v[2:3]
	v_mad_u64_u32 v[170:171], s[4:5], v172, s3, v[2:3]
	v_mov_b32_e32 v171, v7
	v_mov_b32_e32 v169, v7
	v_lshl_add_u64 v[170:171], v[170:171], 2, s[20:21]
	v_lshl_add_u64 v[168:169], v[168:169], 2, s[20:21]
	global_load_dword v170, v[170:171], off
	s_nop 0
	global_load_dword v168, v[168:169], off
	v_lshl_add_u32 v169, v172, 2, v3
	v_lshl_add_u32 v171, v173, 2, v3
	v_add_u32_e32 v174, 0x800, v5
	v_add_u32_e32 v175, 0x800, v4
	v_lshrrev_b32_e32 v178, 3, v175
	v_lshrrev_b32_e32 v179, 3, v174
	v_mad_u64_u32 v[174:175], s[4:5], v179, s3, v[2:3]
	v_mad_u64_u32 v[176:177], s[4:5], v178, s3, v[2:3]
	v_mov_b32_e32 v177, v7
	v_mov_b32_e32 v175, v7
	v_lshl_add_u64 v[176:177], v[176:177], 2, s[20:21]
	v_lshl_add_u64 v[174:175], v[174:175], 2, s[20:21]
	global_load_dword v176, v[176:177], off
	s_nop 0
	global_load_dword v174, v[174:175], off
	v_lshl_add_u32 v175, v178, 2, v3
	v_lshl_add_u32 v177, v179, 2, v3
	v_add_u32_e32 v180, 0xa00, v5
	v_add_u32_e32 v181, 0xa00, v4
	v_lshrrev_b32_e32 v184, 3, v181
	v_lshrrev_b32_e32 v185, 3, v180
	v_mad_u64_u32 v[180:181], s[4:5], v185, s3, v[2:3]
	v_mad_u64_u32 v[182:183], s[4:5], v184, s3, v[2:3]
	v_mov_b32_e32 v183, v7
	v_mov_b32_e32 v181, v7
	v_lshl_add_u64 v[182:183], v[182:183], 2, s[20:21]
	v_lshl_add_u64 v[180:181], v[180:181], 2, s[20:21]
	global_load_dword v182, v[182:183], off
	s_nop 0
	global_load_dword v180, v[180:181], off
	v_lshl_add_u32 v181, v184, 2, v3
	v_lshl_add_u32 v183, v185, 2, v3
	v_add_u32_e32 v186, 0xc00, v5
	v_add_u32_e32 v187, 0xc00, v4
	v_lshrrev_b32_e32 v190, 3, v187
	v_lshrrev_b32_e32 v191, 3, v186
	v_mad_u64_u32 v[186:187], s[4:5], v191, s3, v[2:3]
	v_mad_u64_u32 v[188:189], s[4:5], v190, s3, v[2:3]
	v_mov_b32_e32 v189, v7
	v_mov_b32_e32 v187, v7
	v_lshl_add_u64 v[188:189], v[188:189], 2, s[20:21]
	v_lshl_add_u64 v[186:187], v[186:187], 2, s[20:21]
	global_load_dword v188, v[188:189], off
	s_nop 0
	global_load_dword v186, v[186:187], off
	v_lshl_add_u32 v187, v190, 2, v3
	v_lshl_add_u32 v189, v191, 2, v3
	v_add_u32_e32 v192, 0xe00, v5
	v_add_u32_e32 v193, 0xe00, v4
	v_lshrrev_b32_e32 v196, 3, v193
	v_lshrrev_b32_e32 v197, 3, v192
	v_mad_u64_u32 v[192:193], s[4:5], v197, s3, v[2:3]
	v_mad_u64_u32 v[194:195], s[4:5], v196, s3, v[2:3]
	v_mov_b32_e32 v195, v7
	v_mov_b32_e32 v193, v7
	v_lshl_add_u64 v[194:195], v[194:195], 2, s[20:21]
	v_lshl_add_u64 v[192:193], v[192:193], 2, s[20:21]
	global_load_dword v194, v[194:195], off
	s_nop 0
	global_load_dword v192, v[192:193], off
	v_lshl_add_u32 v193, v196, 2, v3
	v_lshl_add_u32 v195, v197, 2, v3
	v_add_u32_e32 v198, 0x1000, v5
	v_add_u32_e32 v199, 0x1000, v4
	v_lshrrev_b32_e32 v202, 3, v199
	v_lshrrev_b32_e32 v203, 3, v198
	v_mad_u64_u32 v[198:199], s[4:5], v203, s3, v[2:3]
	v_mad_u64_u32 v[200:201], s[4:5], v202, s3, v[2:3]
	v_mov_b32_e32 v201, v7
	v_mov_b32_e32 v199, v7
	v_lshl_add_u64 v[200:201], v[200:201], 2, s[20:21]
	v_lshl_add_u64 v[198:199], v[198:199], 2, s[20:21]
	global_load_dword v200, v[200:201], off
	s_nop 0
	global_load_dword v198, v[198:199], off
	v_lshl_add_u32 v199, v202, 2, v3
	v_lshl_add_u32 v201, v203, 2, v3
	v_add_u32_e32 v204, 0x1200, v5
	v_add_u32_e32 v205, 0x1200, v4
	v_lshrrev_b32_e32 v208, 3, v205
	v_lshrrev_b32_e32 v209, 3, v204
	v_mad_u64_u32 v[204:205], s[4:5], v209, s3, v[2:3]
	v_mad_u64_u32 v[206:207], s[4:5], v208, s3, v[2:3]
	v_mov_b32_e32 v207, v7
	v_mov_b32_e32 v205, v7
	v_lshl_add_u64 v[206:207], v[206:207], 2, s[20:21]
	v_lshl_add_u64 v[204:205], v[204:205], 2, s[20:21]
	global_load_dword v206, v[206:207], off
	s_nop 0
	global_load_dword v204, v[204:205], off
	v_lshl_add_u32 v205, v208, 2, v3
	v_lshl_add_u32 v207, v209, 2, v3
; DI void phase_prep(const Params& p, int bid, int nb, char* smem) {
;     ...
;   for (int i = tid; i < 8192; i += 256) { int k = i >> 3, j = i & 7; wabT[j * 1024 + k] = p.w_in[(size_t)k * INC + 3584 + j]; }
	v_add_u32_e32 v210, 0x1400, v5
	v_add_u32_e32 v211, 0x1400, v4
	v_lshrrev_b32_e32 v214, 3, v211
	v_lshrrev_b32_e32 v215, 3, v210
	v_mad_u64_u32 v[210:211], s[4:5], v215, s3, v[2:3]
	v_mad_u64_u32 v[212:213], s[4:5], v214, s3, v[2:3]
	v_mov_b32_e32 v213, v7
	v_mov_b32_e32 v211, v7
	v_lshl_add_u64 v[212:213], v[212:213], 2, s[20:21]
	v_lshl_add_u64 v[210:211], v[210:211], 2, s[20:21]
	global_load_dword v212, v[212:213], off
	s_nop 0
	global_load_dword v210, v[210:211], off
	v_lshl_add_u32 v211, v214, 2, v3
	v_lshl_add_u32 v213, v215, 2, v3
	v_add_u32_e32 v216, 0x1600, v5
	v_add_u32_e32 v217, 0x1600, v4
	v_lshrrev_b32_e32 v220, 3, v217
	v_lshrrev_b32_e32 v221, 3, v216
	v_mad_u64_u32 v[216:217], s[4:5], v221, s3, v[2:3]
	v_mad_u64_u32 v[218:219], s[4:5], v220, s3, v[2:3]
	v_mov_b32_e32 v219, v7
	v_mov_b32_e32 v217, v7
	v_lshl_add_u64 v[218:219], v[218:219], 2, s[20:21]
	v_lshl_add_u64 v[216:217], v[216:217], 2, s[20:21]
	global_load_dword v218, v[218:219], off
	s_nop 0
	global_load_dword v216, v[216:217], off
	v_lshl_add_u32 v217, v220, 2, v3
	v_lshl_add_u32 v219, v221, 2, v3
	v_add_u32_e32 v222, 0x1800, v5
	v_add_u32_e32 v223, 0x1800, v4
	v_lshrrev_b32_e32 v226, 3, v223
	v_lshrrev_b32_e32 v227, 3, v222
	v_mad_u64_u32 v[222:223], s[4:5], v227, s3, v[2:3]
	v_mad_u64_u32 v[224:225], s[4:5], v226, s3, v[2:3]
	v_mov_b32_e32 v225, v7
	v_mov_b32_e32 v223, v7
	v_lshl_add_u64 v[224:225], v[224:225], 2, s[20:21]
	v_lshl_add_u64 v[222:223], v[222:223], 2, s[20:21]
	global_load_dword v224, v[224:225], off
	s_nop 0
	global_load_dword v222, v[222:223], off
	v_lshl_add_u32 v223, v226, 2, v3
	v_lshl_add_u32 v225, v227, 2, v3
	v_add_u32_e32 v228, 0x1a00, v5
	v_add_u32_e32 v229, 0x1a00, v4
	v_lshrrev_b32_e32 v232, 3, v229
	v_lshrrev_b32_e32 v233, 3, v228
	v_mad_u64_u32 v[228:229], s[4:5], v233, s3, v[2:3]
	v_mad_u64_u32 v[230:231], s[4:5], v232, s3, v[2:3]
	v_mov_b32_e32 v231, v7
	v_mov_b32_e32 v229, v7
	v_lshl_add_u64 v[230:231], v[230:231], 2, s[20:21]
	v_lshl_add_u64 v[228:229], v[228:229], 2, s[20:21]
	global_load_dword v230, v[230:231], off
	s_nop 0
	global_load_dword v228, v[228:229], off
	v_lshl_add_u32 v229, v232, 2, v3
	v_lshl_add_u32 v231, v233, 2, v3
	v_add_u32_e32 v234, 0x1c00, v5
	v_add_u32_e32 v235, 0x1c00, v4
	v_lshrrev_b32_e32 v238, 3, v235
	v_lshrrev_b32_e32 v239, 3, v234
	v_mad_u64_u32 v[234:235], s[4:5], v239, s3, v[2:3]
	v_mad_u64_u32 v[236:237], s[4:5], v238, s3, v[2:3]
	v_mov_b32_e32 v237, v7
	v_mov_b32_e32 v235, v7
	v_lshl_add_u64 v[236:237], v[236:237], 2, s[20:21]
	v_lshl_add_u64 v[234:235], v[234:235], 2, s[20:21]
	global_load_dword v236, v[236:237], off
	s_nop 0
	global_load_dword v234, v[234:235], off
	v_lshl_add_u32 v235, v238, 2, v3
	v_lshl_add_u32 v237, v239, 2, v3
	v_add_u32_e32 v240, 0x1e00, v5
	v_add_u32_e32 v241, 0x1e00, v4
	v_lshrrev_b32_e32 v244, 3, v241
	v_lshrrev_b32_e32 v245, 3, v240
	v_mad_u64_u32 v[240:241], s[4:5], v245, s3, v[2:3]
	v_mad_u64_u32 v[242:243], s[4:5], v244, s3, v[2:3]
	v_mov_b32_e32 v243, v7
	v_mov_b32_e32 v241, v7
	v_lshl_add_u64 v[242:243], v[242:243], 2, s[20:21]
	v_lshl_add_u64 v[240:241], v[240:241], 2, s[20:21]
	global_load_dword v242, v[242:243], off
	s_nop 0
	global_load_dword v240, v[240:241], off
	v_lshl_add_u32 v241, v244, 2, v3
	v_lshl_add_u32 v243, v245, 2, v3
	v_add_u32_e32 v5, 0x2000, v5
	v_add_u32_e32 v4, 0x2000, v4
	s_waitcnt vmcnt(31)
	ds_write_b32 v151, v152 offset:256
	s_waitcnt vmcnt(30)
	ds_write_b32 v153, v150 offset:256
	s_waitcnt vmcnt(29)
	ds_write_b32 v157, v158 offset:256
	s_waitcnt vmcnt(28)
	ds_write_b32 v159, v156 offset:256
	s_waitcnt vmcnt(27)
	ds_write_b32 v163, v164 offset:256
	s_waitcnt vmcnt(26)
	ds_write_b32 v165, v162 offset:256
	s_waitcnt vmcnt(25)
	ds_write_b32 v169, v170 offset:256
	s_waitcnt vmcnt(24)
	ds_write_b32 v171, v168 offset:256
	s_waitcnt vmcnt(23)
	ds_write_b32 v175, v176 offset:256
	s_waitcnt vmcnt(22)
	ds_write_b32 v177, v174 offset:256
	s_waitcnt vmcnt(21)
	ds_write_b32 v181, v182 offset:256
	s_waitcnt vmcnt(20)
	ds_write_b32 v183, v180 offset:256
	s_waitcnt vmcnt(19)
	ds_write_b32 v187, v188 offset:256
	s_waitcnt vmcnt(18)
	ds_write_b32 v189, v186 offset:256
	s_waitcnt vmcnt(17)
	ds_write_b32 v193, v194 offset:256
	s_waitcnt vmcnt(16)
	ds_write_b32 v195, v192 offset:256
	s_waitcnt vmcnt(15)
	ds_write_b32 v199, v200 offset:256
	s_waitcnt vmcnt(14)
	ds_write_b32 v201, v198 offset:256
	s_waitcnt vmcnt(13)
	ds_write_b32 v205, v206 offset:256
	s_waitcnt vmcnt(12)
	ds_write_b32 v207, v204 offset:256
	s_waitcnt vmcnt(11)
	ds_write_b32 v211, v212 offset:256
	s_waitcnt vmcnt(10)
	ds_write_b32 v213, v210 offset:256
	s_waitcnt vmcnt(9)
	ds_write_b32 v217, v218 offset:256
	s_waitcnt vmcnt(8)
	ds_write_b32 v219, v216 offset:256
	s_waitcnt vmcnt(7)
	ds_write_b32 v223, v224 offset:256
	s_waitcnt vmcnt(6)
	ds_write_b32 v225, v222 offset:256
	s_waitcnt vmcnt(5)
	ds_write_b32 v229, v230 offset:256
	s_waitcnt vmcnt(4)
	ds_write_b32 v231, v228 offset:256
	s_waitcnt vmcnt(3)
	ds_write_b32 v235, v236 offset:256
	s_waitcnt vmcnt(2)
	ds_write_b32 v237, v234 offset:256
	s_waitcnt vmcnt(1)
	ds_write_b32 v241, v242 offset:256
	s_waitcnt vmcnt(0)
	ds_write_b32 v243, v240 offset:256
	s_or_b64 exec, exec, s[0:1]
	v_mov_b32_e32 v6, 0
	v_cmp_ne_u32_e64 s[4:5], 0, 0
	s_and_saveexec_b64 s[0:1], s[4:5]
	s_cbranch_execz .LBB0_13
	s_mov_b64 s[4:5], 0
	s_movk_i32 s3, 0xe08
	v_mov_b32_e32 v7, 0

; DI void transpose_items(const float* src, int ld, int ncols, u16* dst, int bid, int nb, float* tile) {
;     ...
;   for (int it = bid; it < nitems; it += nb) {
;     const int k0 = (it / ntn) * 64, n0 = (it % ntn) * 64;
;     __syncthreads();
; #pragma unroll
;     for (int i = 0; i < 4; i++) {
;       int r = (tid >> 4) + 16 * i, c = (tid & 15) * 4;
;       const f32x4 v = __builtin_nontemporal_load((const f32x4*)(src + (size_t)(k0 + r) * ld + n0 + c));
;       tile[r * 65 + c] = v[0]; tile[r * 65 + c + 1] = v[1]; tile[r * 65 + c + 2] = v[2]; tile[r * 65 + c + 3] = v[3];
;     }
;     __syncthreads();
.LBB0_32:
	s_mul_hi_i32 s0, s8, 0x92492493
	s_add_i32 s0, s0, s8
	s_lshr_b32 s1, s0, 31
	s_ashr_i32 s0, s0, 5
	s_add_i32 s0, s0, s1
	s_lshl_b32 s4, s0, 6
	s_mulk_i32 s0, 0xf200
	s_add_i32 s0, s3, s0
	s_ashr_i32 s1, s0, 31
	v_lshl_add_u64 v[22:23], s[0:1], 2, v[2:3]
	v_or_b32_e32 v25, s4, v1
	v_mad_i64_i32 v[26:27], s[10:11], v25, s7, v[22:23]
	global_load_dwordx4 v[26:29], v[26:27], off nt
	v_add_u32_e32 v25, s4, v9
	v_add_u32_e32 v46, s0, v6
	s_ashr_i32 s5, s4, 31
	v_ashrrev_i32_e32 v47, 31, v46
	v_lshlrev_b64 v[48:49], 11, v[46:47]
	s_add_i32 s8, s8, s16
	s_add_i32 s3, s3, s6
	s_cmpk_lt_i32 s8, 0x380
	v_mad_i64_i32 v[136:137], s[10:11], v25, s7, v[22:23]
	global_load_dwordx4 v[136:139], v[136:137], off nt
	v_add_u32_e32 v25, s4, v10
	v_mad_i64_i32 v[140:141], s[10:11], v25, s7, v[22:23]
	global_load_dwordx4 v[140:143], v[140:141], off nt
	v_add_u32_e32 v25, s4, v11
	v_mad_i64_i32 v[22:23], s[10:11], v25, s7, v[22:23]
	global_load_dwordx4 v[144:147], v[22:23], off nt
	v_lshl_add_u64 v[22:23], s[4:5], 1, v[4:5]
	v_lshl_add_u64 v[48:49], v[22:23], 0, v[48:49]
	s_barrier
	s_waitcnt vmcnt(3)
	ds_write2_b32 v12, v26, v27 offset0:64 offset1:65
	ds_write2_b32 v12, v28, v29 offset0:66 offset1:67
	s_waitcnt vmcnt(2)
	ds_write2_b32 v13, v136, v137 offset1:1
	ds_write2_b32 v14, v138, v139 offset1:1
	s_waitcnt vmcnt(1)
	ds_write2_b32 v15, v140, v141 offset1:1
	ds_write2_b32 v16, v142, v143 offset1:1
	s_waitcnt vmcnt(0)
	ds_write2_b32 v17, v144, v145 offset1:1
	ds_write2_b32 v18, v146, v147 offset1:1
	s_waitcnt lgkmcnt(0)
	s_barrier
	ds_read2_b32 v[30:31], v19 offset0:64 offset1:96
	ds_read2_b32 v[32:33], v19 offset0:129 offset1:161
	ds_read2_b32 v[34:35], v19 offset0:194 offset1:226
	ds_read2_b32 v[36:37], v20 offset0:3 offset1:35
	ds_read2_b32 v[38:39], v20 offset0:68 offset1:100
	ds_read2_b32 v[40:41], v20 offset0:133 offset1:165
	ds_read2_b32 v[42:43], v20 offset0:198 offset1:230
	ds_read2_b32 v[44:45], v21 offset0:7 offset1:39
	s_waitcnt lgkmcnt(6)
	v_cvt_pk_bf16_f32 v26, v30, v32
	s_waitcnt lgkmcnt(4)
	v_cvt_pk_bf16_f32 v27, v34, v36
	s_waitcnt lgkmcnt(2)
	v_cvt_pk_bf16_f32 v28, v38, v40
	v_add_u32_e32 v30, 32, v46
	s_waitcnt lgkmcnt(0)
	v_cvt_pk_bf16_f32 v29, v42, v44
	global_store_dwordx4 v[48:49], v[26:29], off
	s_nop 1
	v_cvt_pk_bf16_f32 v26, v31, v33
	v_ashrrev_i32_e32 v31, 31, v30
	v_lshlrev_b64 v[30:31], 11, v[30:31]
	v_cvt_pk_bf16_f32 v27, v35, v37
	v_cvt_pk_bf16_f32 v28, v39, v41
	v_cvt_pk_bf16_f32 v29, v43, v45
	v_lshl_add_u64 v[22:23], v[22:23], 0, v[30:31]
	global_store_dwordx4 v[22:23], v[26:29], off
	s_cbranch_scc1 .LBB0_32

; DI void transpose_items(const float* src, int ld, int ncols, u16* dst, int bid, int nb, float* tile) {
;     ...
;   for (int it = bid; it < nitems; it += nb) {
;     const int k0 = (it / ntn) * 64, n0 = (it % ntn) * 64;
;     __syncthreads();
; #pragma unroll
;     for (int i = 0; i < 4; i++) {
;       int r = (tid >> 4) + 16 * i, c = (tid & 15) * 4;
;       const f32x4 v = __builtin_nontemporal_load((const f32x4*)(src + (size_t)(k0 + r) * ld + n0 + c));
;       tile[r * 65 + c] = v[0]; tile[r * 65 + c + 1] = v[1]; tile[r * 65 + c + 2] = v[2]; tile[r * 65 + c + 3] = v[3];
;     }
;     __syncthreads();
.LBB0_35:
	s_ashr_i32 s0, s7, 31
	s_lshr_b32 s0, s0, 28
	s_add_i32 s0, s7, s0
	s_ashr_i32 s0, s0, 4
	s_lshl_b32 s4, s0, 6
	s_lshl_b32 s0, s0, 10
	s_sub_i32 s0, s3, s0
	v_or_b32_e32 v26, s4, v1
	s_ashr_i32 s1, s0, 31
	v_ashrrev_i32_e32 v27, 31, v26
	v_lshl_add_u64 v[22:23], s[0:1], 2, v[2:3]
	v_lshlrev_b64 v[26:27], 12, v[26:27]
	v_lshl_add_u64 v[26:27], v[22:23], 0, v[26:27]
	global_load_dwordx4 v[26:29], v[26:27], off nt
	v_add_u32_e32 v46, s0, v6
	s_ashr_i32 s5, s4, 31
	v_ashrrev_i32_e32 v47, 31, v46
	v_lshlrev_b64 v[48:49], 11, v[46:47]
	s_add_i32 s7, s7, s8
	s_add_i32 s3, s3, s6
	s_cmpk_lt_i32 s7, 0x100
	v_add_u32_e32 v136, s4, v9
	v_ashrrev_i32_e32 v137, 31, v136
	v_lshlrev_b64 v[136:137], 12, v[136:137]
	v_lshl_add_u64 v[136:137], v[22:23], 0, v[136:137]
	global_load_dwordx4 v[136:139], v[136:137], off nt
	v_add_u32_e32 v140, s4, v10
	v_ashrrev_i32_e32 v141, 31, v140
	v_lshlrev_b64 v[140:141], 12, v[140:141]
	v_lshl_add_u64 v[140:141], v[22:23], 0, v[140:141]
	global_load_dwordx4 v[140:143], v[140:141], off nt
	v_add_u32_e32 v144, s4, v11
	v_ashrrev_i32_e32 v145, 31, v144
	v_lshlrev_b64 v[144:145], 12, v[144:145]
	v_lshl_add_u64 v[22:23], v[22:23], 0, v[144:145]
	global_load_dwordx4 v[144:147], v[22:23], off nt
	v_lshl_add_u64 v[22:23], s[4:5], 1, v[4:5]
	v_lshl_add_u64 v[48:49], v[22:23], 0, v[48:49]
	s_barrier
	s_waitcnt vmcnt(3)
	ds_write2_b32 v12, v26, v27 offset0:64 offset1:65
	ds_write2_b32 v12, v28, v29 offset0:66 offset1:67
	s_waitcnt vmcnt(2)
	ds_write2_b32 v13, v136, v137 offset1:1
	ds_write2_b32 v14, v138, v139 offset1:1
	s_waitcnt vmcnt(1)
	ds_write2_b32 v15, v140, v141 offset1:1
	ds_write2_b32 v16, v142, v143 offset1:1
	s_waitcnt vmcnt(0)
	ds_write2_b32 v17, v144, v145 offset1:1
	ds_write2_b32 v18, v146, v147 offset1:1
	s_waitcnt lgkmcnt(0)
	s_barrier
	ds_read2_b32 v[30:31], v19 offset0:64 offset1:96
	ds_read2_b32 v[32:33], v19 offset0:129 offset1:161
	ds_read2_b32 v[34:35], v19 offset0:194 offset1:226
	ds_read2_b32 v[36:37], v20 offset0:3 offset1:35
	ds_read2_b32 v[38:39], v20 offset0:68 offset1:100
	ds_read2_b32 v[40:41], v20 offset0:133 offset1:165
	ds_read2_b32 v[42:43], v20 offset0:198 offset1:230
	ds_read2_b32 v[44:45], v21 offset0:7 offset1:39
	s_waitcnt lgkmcnt(6)
	v_cvt_pk_bf16_f32 v26, v30, v32
	s_waitcnt lgkmcnt(4)
	v_cvt_pk_bf16_f32 v27, v34, v36
	s_waitcnt lgkmcnt(2)
	v_cvt_pk_bf16_f32 v28, v38, v40
	v_add_u32_e32 v30, 32, v46
	s_waitcnt lgkmcnt(0)
	v_cvt_pk_bf16_f32 v29, v42, v44
	global_store_dwordx4 v[48:49], v[26:29], off
	s_nop 1
	v_cvt_pk_bf16_f32 v26, v31, v33
	v_ashrrev_i32_e32 v31, 31, v30
	v_lshlrev_b64 v[30:31], 11, v[30:31]
	v_cvt_pk_bf16_f32 v27, v35, v37
	v_cvt_pk_bf16_f32 v28, v39, v41
	v_cvt_pk_bf16_f32 v29, v43, v45
	v_lshl_add_u64 v[22:23], v[22:23], 0, v[30:31]
	global_store_dwordx4 v[22:23], v[26:29], off
	s_cbranch_scc1 .LBB0_35

; DI void transpose_items(const float* src, int ld, int ncols, u16* dst, int bid, int nb, float* tile) {
;     ...
;   for (int it = bid; it < nitems; it += nb) {
;     const int k0 = (it / ntn) * 64, n0 = (it % ntn) * 64;
;     __syncthreads();
; #pragma unroll
;     for (int i = 0; i < 4; i++) {
;       int r = (tid >> 4) + 16 * i, c = (tid & 15) * 4;
;       const f32x4 v = __builtin_nontemporal_load((const f32x4*)(src + (size_t)(k0 + r) * ld + n0 + c));
;       tile[r * 65 + c] = v[0]; tile[r * 65 + c + 1] = v[1]; tile[r * 65 + c + 2] = v[2]; tile[r * 65 + c + 3] = v[3];
;     }
;     __syncthreads();
.LBB0_38:
	s_ashr_i32 s0, s7, 31
	s_lshr_b32 s0, s0, 27
	s_add_i32 s0, s7, s0
	s_ashr_i32 s0, s0, 5
	s_lshl_b32 s4, s0, 6
	s_lshl_b32 s0, s0, 11
	s_sub_i32 s0, s3, s0
	v_or_b32_e32 v20, s4, v1
	s_ashr_i32 s1, s0, 31
	v_ashrrev_i32_e32 v21, 31, v20
	v_lshl_add_u64 v[26:27], s[0:1], 2, v[2:3]
	v_lshlrev_b64 v[20:21], 13, v[20:21]
	v_lshl_add_u64 v[20:21], v[26:27], 0, v[20:21]
	global_load_dwordx4 v[20:23], v[20:21], off nt
	v_add_u32_e32 v44, s0, v6
	s_ashr_i32 s5, s4, 31
	v_ashrrev_i32_e32 v45, 31, v44
	v_lshlrev_b64 v[46:47], 11, v[44:45]
	s_add_i32 s7, s7, s8
	s_add_i32 s3, s3, s6
	s_cmpk_lt_i32 s7, 0x200
	v_add_u32_e32 v136, s4, v7
	v_ashrrev_i32_e32 v137, 31, v136
	v_lshlrev_b64 v[136:137], 13, v[136:137]
	v_lshl_add_u64 v[136:137], v[26:27], 0, v[136:137]
	global_load_dwordx4 v[136:139], v[136:137], off nt
	v_add_u32_e32 v140, s4, v8
	v_ashrrev_i32_e32 v141, 31, v140
	v_lshlrev_b64 v[140:141], 13, v[140:141]
	v_lshl_add_u64 v[140:141], v[26:27], 0, v[140:141]
	global_load_dwordx4 v[140:143], v[140:141], off nt
	v_add_u32_e32 v144, s4, v9
	v_ashrrev_i32_e32 v145, 31, v144
	v_lshlrev_b64 v[144:145], 13, v[144:145]
	v_lshl_add_u64 v[144:145], v[26:27], 0, v[144:145]
	global_load_dwordx4 v[144:147], v[144:145], off nt
	v_lshl_add_u64 v[26:27], s[4:5], 1, v[4:5]
	v_lshl_add_u64 v[46:47], v[26:27], 0, v[46:47]
	s_barrier
	s_waitcnt vmcnt(3)
	ds_write2_b32 v10, v20, v21 offset0:64 offset1:65
	ds_write2_b32 v10, v22, v23 offset0:66 offset1:67
	s_waitcnt vmcnt(2)
	ds_write2_b32 v11, v136, v137 offset1:1
	ds_write2_b32 v12, v138, v139 offset1:1
	s_waitcnt vmcnt(1)
	ds_write2_b32 v13, v140, v141 offset1:1
	ds_write2_b32 v14, v142, v143 offset1:1
	s_waitcnt vmcnt(0)
	ds_write2_b32 v15, v144, v145 offset1:1
	ds_write2_b32 v16, v146, v147 offset1:1
	s_waitcnt lgkmcnt(0)
	s_barrier
	ds_read2_b32 v[28:29], v17 offset0:64 offset1:96
	ds_read2_b32 v[30:31], v17 offset0:129 offset1:161
	ds_read2_b32 v[32:33], v17 offset0:194 offset1:226
	ds_read2_b32 v[34:35], v18 offset0:3 offset1:35
	ds_read2_b32 v[36:37], v18 offset0:68 offset1:100
	ds_read2_b32 v[38:39], v18 offset0:133 offset1:165
	ds_read2_b32 v[40:41], v18 offset0:198 offset1:230
	ds_read2_b32 v[42:43], v19 offset0:7 offset1:39
	s_waitcnt lgkmcnt(6)
	v_cvt_pk_bf16_f32 v20, v28, v30
	s_waitcnt lgkmcnt(4)
	v_cvt_pk_bf16_f32 v21, v32, v34
	s_waitcnt lgkmcnt(2)
	v_cvt_pk_bf16_f32 v22, v36, v38
	v_add_u32_e32 v28, 32, v44
	s_waitcnt lgkmcnt(0)
	v_cvt_pk_bf16_f32 v23, v40, v42
	global_store_dwordx4 v[46:47], v[20:23], off
	s_nop 1
	v_cvt_pk_bf16_f32 v20, v29, v31
	v_ashrrev_i32_e32 v29, 31, v28
	v_lshlrev_b64 v[28:29], 11, v[28:29]
	v_cvt_pk_bf16_f32 v21, v33, v35
	v_cvt_pk_bf16_f32 v22, v37, v39
	v_cvt_pk_bf16_f32 v23, v41, v43
	v_lshl_add_u64 v[26:27], v[26:27], 0, v[28:29]
	global_store_dwordx4 v[26:27], v[20:23], off
	s_cbranch_scc1 .LBB0_38
